# v17 with the regenerated SwiGLU block re-ordered: transcendental ops (exp, rcp) alternate with the packed f32 ops instead of running in batches
# baseline (speedup 1.0000x reference)
; __device__ __forceinline__ unsigned cvt_pk_bf16(float lo, float hi) { unsigned r; asm volatile("v_cvt_pk_bf16_f32 %0, %1, %2" : "=v"(r) : "v"(lo), "v"(hi)); return r; }
; __device__ __forceinline__ float silu_f(float g) { return g * __builtin_amdgcn_rcpf(1.0f + __expf(-g)); }
; __device__ __forceinline__ float row_rstd(const float* rss, int row) { if (!rss) return 1.0f; const f32x4 s = *(const f32x4*)(rss + 4 * (size_t)row); return __builtin_amdgcn_rsqf(((s[0] + s[1]) + (s[2] + s[3])) * (1.0f / 1024.0f) + 1e-6f); }
;     __device__ __forceinline__ void operator()(const f32x4 (&acc)[2][2][4][2], const Unit& u, int wr, int wc, int fr, int fq) const {
;     ...
;             for (int m = 0; m < 4; ++m) { const int row = row0 + ai * HALF + m * 16; bf16_t* rowp = O + (size_t)row * ldc + col0; const float rs = row_rstd(rss, row);
;                 const f32x4 g0 = acc[ai][0][m][0] * rs, g1 = acc[ai][0][m][1] * rs, u0 = acc[ai][1][m][0] * rs, u1 = acc[ai][1][m][1] * rs;
;                 u32x4 w;
;                 w.x = cvt_pk_bf16(silu_f(g0[0]) * u0[0], silu_f(g0[1]) * u0[1]); w.y = cvt_pk_bf16(silu_f(g0[2]) * u0[2], silu_f(g0[3]) * u0[3]);
;                 w.z = cvt_pk_bf16(silu_f(g1[0]) * u1[0], silu_f(g1[1]) * u1[1]); w.w = cvt_pk_bf16(silu_f(g1[2]) * u1[2], silu_f(g1[3]) * u1[3]);
;                 *(u32x4*)rowp = w; }
.LBB0_211:
	v_lshl_or_b32 v148, s0, 7, v159
	v_lshl_add_u32 v150, s1, 8, v1
	v_add_u32_e32 v194, 0, v150
	v_ashrrev_i32_e32 v195, 31, v194
	v_lshl_add_u64 v[194:195], v[194:195], 4, s[22:23]
	global_load_dwordx4 v[194:197], v[194:195], off
	v_add_u32_e32 v198, 16, v150
	v_ashrrev_i32_e32 v199, 31, v198
	v_lshl_add_u64 v[198:199], v[198:199], 4, s[22:23]
	global_load_dwordx4 v[198:201], v[198:199], off
	v_add_u32_e32 v202, 32, v150
	v_ashrrev_i32_e32 v203, 31, v202
	v_lshl_add_u64 v[202:203], v[202:203], 4, s[22:23]
	global_load_dwordx4 v[202:205], v[202:203], off
	v_add_u32_e32 v206, 48, v150
	v_ashrrev_i32_e32 v207, 31, v206
	v_lshl_add_u64 v[206:207], v[206:207], 4, s[22:23]
	global_load_dwordx4 v[206:209], v[206:207], off
	v_add_u32_e32 v210, 128, v150
	v_ashrrev_i32_e32 v211, 31, v210
	v_lshl_add_u64 v[210:211], v[210:211], 4, s[22:23]
	global_load_dwordx4 v[210:213], v[210:211], off
	v_add_u32_e32 v214, 144, v150
	v_ashrrev_i32_e32 v215, 31, v214
	v_lshl_add_u64 v[214:215], v[214:215], 4, s[22:23]
	global_load_dwordx4 v[214:217], v[214:215], off
	v_add_u32_e32 v218, 160, v150
	v_ashrrev_i32_e32 v219, 31, v218
	v_lshl_add_u64 v[218:219], v[218:219], 4, s[22:23]
	global_load_dwordx4 v[218:221], v[218:219], off
	v_add_u32_e32 v222, 176, v150
	v_ashrrev_i32_e32 v223, 31, v222
	v_lshl_add_u64 v[222:223], v[222:223], 4, s[22:23]
	global_load_dwordx4 v[222:225], v[222:223], off
	v_ashrrev_i32_e32 v149, 31, v148
	v_mov_b64_e32 v[146:147], s[20:21]
	v_ashrrev_i32_e32 v151, 31, v150
	v_mad_i64_i32 v[162:163], s[0:1], v150, s4, v[146:147]
	v_lshlrev_b64 v[148:149], 1, v[148:149]
	v_lshl_add_u64 v[166:167], v[162:163], 0, v[148:149]
	v_lshl_add_u64 v[162:163], v[150:151], 4, s[22:23]
	s_mov_b64 s[30:31], -1
	s_and_b64 vcc, exec, s[8:9]
	s_waitcnt vmcnt(7)
	v_mov_b64_e32 v[162:163], v[194:195]
	v_mov_b64_e32 v[164:165], v[196:197]
	v_mov_b32_e32 v168, v163
	v_mov_b32_e32 v169, v164
	v_mov_b32_e32 v163, v165
	v_pk_add_f32 v[162:163], v[168:169], v[162:163]
	s_nop 0
	v_add_f32_e32 v151, v162, v163
	v_fmamk_f32 v151, v151, 0x3a800000, v138
	v_rsq_f32_e32 v162, v151
	s_nop 0
	v_mul_f32_e32 v244, 0xbfb8aa3b, v162
	v_mul_f32_e32 v246, v162, v162
	v_mov_b32_e32 v248, 1.0
	v_pk_mul_f32 v[228:229], v[122:123], v[244:245] op_sel_hi:[1,0]
	v_pk_mul_f32 v[232:233], v[124:125], v[244:245] op_sel_hi:[1,0]
	v_exp_f32_e32 v228, v228
	v_pk_mul_f32 v[236:237], v[126:127], v[244:245] op_sel_hi:[1,0]
	v_exp_f32_e32 v229, v229
	v_pk_mul_f32 v[240:241], v[128:129], v[244:245] op_sel_hi:[1,0]
	v_exp_f32_e32 v232, v232
	v_pk_mul_f32 v[230:231], v[122:123], v[118:119]
	v_exp_f32_e32 v233, v233
	v_pk_mul_f32 v[234:235], v[124:125], v[120:121]
	v_exp_f32_e32 v236, v236
	v_pk_mul_f32 v[238:239], v[126:127], v[114:115]
	v_exp_f32_e32 v237, v237
	v_pk_mul_f32 v[242:243], v[128:129], v[116:117]
	v_exp_f32_e32 v240, v240
	v_pk_add_f32 v[228:229], v[228:229], v[248:249] op_sel_hi:[1,0]
	v_exp_f32_e32 v241, v241
	v_pk_add_f32 v[232:233], v[232:233], v[248:249] op_sel_hi:[1,0]
	v_rcp_f32_e32 v228, v228
	v_pk_add_f32 v[236:237], v[236:237], v[248:249] op_sel_hi:[1,0]
	v_rcp_f32_e32 v229, v229
	v_pk_add_f32 v[240:241], v[240:241], v[248:249] op_sel_hi:[1,0]
	v_rcp_f32_e32 v232, v232
	v_pk_mul_f32 v[230:231], v[230:231], v[246:247] op_sel_hi:[1,0]
	v_rcp_f32_e32 v233, v233
	v_pk_mul_f32 v[234:235], v[234:235], v[246:247] op_sel_hi:[1,0]
	v_rcp_f32_e32 v236, v236
	v_pk_mul_f32 v[238:239], v[238:239], v[246:247] op_sel_hi:[1,0]
	v_rcp_f32_e32 v237, v237
	v_pk_mul_f32 v[242:243], v[242:243], v[246:247] op_sel_hi:[1,0]
	v_rcp_f32_e32 v240, v240
	v_pk_mul_f32 v[230:231], v[230:231], v[228:229]
	v_rcp_f32_e32 v241, v241
	v_pk_mul_f32 v[234:235], v[234:235], v[232:233]
	v_cvt_pk_bf16_f32 v114, v230, v231
	v_pk_mul_f32 v[238:239], v[238:239], v[236:237]
	v_cvt_pk_bf16_f32 v115, v234, v235
	v_pk_mul_f32 v[242:243], v[242:243], v[240:241]
	v_cvt_pk_bf16_f32 v116, v238, v239
	s_nop 0
	v_cvt_pk_bf16_f32 v117, v242, v243
	global_store_dwordx4 v[166:167], v[114:117], off
	s_nop 1
	v_or_b32_e32 v116, 16, v150
	v_ashrrev_i32_e32 v117, 31, v116
	v_mad_i64_i32 v[114:115], s[0:1], v116, s4, v[146:147]
	v_lshl_add_u64 v[116:117], v[116:117], 4, s[22:23]
	v_lshl_add_u64 v[114:115], v[114:115], 0, v[148:149]
	s_waitcnt vmcnt(7)
	v_mov_b64_e32 v[116:117], v[198:199]
	v_mov_b64_e32 v[118:119], v[200:201]
	v_mov_b32_e32 v120, v117
	v_mov_b32_e32 v121, v118
	v_mov_b32_e32 v117, v119
	v_pk_add_f32 v[116:117], v[120:121], v[116:117]
	s_nop 0
	v_add_f32_e32 v116, v116, v117
	v_fmamk_f32 v116, v116, 0x3a800000, v138
	v_rsq_f32_e32 v116, v116
	s_nop 0
	v_mul_f32_e32 v244, 0xbfb8aa3b, v116
	v_mul_f32_e32 v246, v116, v116
	v_mov_b32_e32 v248, 1.0
	v_pk_mul_f32 v[228:229], v[110:111], v[244:245] op_sel_hi:[1,0]
	v_pk_mul_f32 v[232:233], v[112:113], v[244:245] op_sel_hi:[1,0]
	v_exp_f32_e32 v228, v228
	v_pk_mul_f32 v[236:237], v[106:107], v[244:245] op_sel_hi:[1,0]
	v_exp_f32_e32 v229, v229
	v_pk_mul_f32 v[240:241], v[108:109], v[244:245] op_sel_hi:[1,0]
	v_exp_f32_e32 v232, v232
	v_pk_mul_f32 v[230:231], v[110:111], v[102:103]
	v_exp_f32_e32 v233, v233
	v_pk_mul_f32 v[234:235], v[112:113], v[104:105]
	v_exp_f32_e32 v236, v236
	v_pk_mul_f32 v[238:239], v[106:107], v[98:99]
	v_exp_f32_e32 v237, v237
	v_pk_mul_f32 v[242:243], v[108:109], v[100:101]
	v_exp_f32_e32 v240, v240
	v_pk_add_f32 v[228:229], v[228:229], v[248:249] op_sel_hi:[1,0]
	v_exp_f32_e32 v241, v241
	v_pk_add_f32 v[232:233], v[232:233], v[248:249] op_sel_hi:[1,0]
	v_rcp_f32_e32 v228, v228
	v_pk_add_f32 v[236:237], v[236:237], v[248:249] op_sel_hi:[1,0]
	v_rcp_f32_e32 v229, v229
	v_pk_add_f32 v[240:241], v[240:241], v[248:249] op_sel_hi:[1,0]
	v_rcp_f32_e32 v232, v232
	v_pk_mul_f32 v[230:231], v[230:231], v[246:247] op_sel_hi:[1,0]
	v_rcp_f32_e32 v233, v233
	v_pk_mul_f32 v[234:235], v[234:235], v[246:247] op_sel_hi:[1,0]
	v_rcp_f32_e32 v236, v236
	v_pk_mul_f32 v[238:239], v[238:239], v[246:247] op_sel_hi:[1,0]
	v_rcp_f32_e32 v237, v237
	v_pk_mul_f32 v[242:243], v[242:243], v[246:247] op_sel_hi:[1,0]
	v_rcp_f32_e32 v240, v240
	v_pk_mul_f32 v[230:231], v[230:231], v[228:229]
	v_rcp_f32_e32 v241, v241
	v_pk_mul_f32 v[234:235], v[234:235], v[232:233]
	v_cvt_pk_bf16_f32 v98, v230, v231
	v_pk_mul_f32 v[238:239], v[238:239], v[236:237]
	v_cvt_pk_bf16_f32 v99, v234, v235
	v_pk_mul_f32 v[242:243], v[242:243], v[240:241]
	v_cvt_pk_bf16_f32 v100, v238, v239
	s_nop 0
	v_cvt_pk_bf16_f32 v101, v242, v243
	global_store_dwordx4 v[114:115], v[98:101], off
	s_nop 1
	v_or_b32_e32 v100, 32, v150
	v_ashrrev_i32_e32 v101, 31, v100
	v_mad_i64_i32 v[98:99], s[0:1], v100, s4, v[146:147]
	v_lshl_add_u64 v[100:101], v[100:101], 4, s[22:23]
	v_lshl_add_u64 v[98:99], v[98:99], 0, v[148:149]
	s_waitcnt vmcnt(7)
; __device__ __forceinline__ unsigned cvt_pk_bf16(float lo, float hi) { unsigned r; asm volatile("v_cvt_pk_bf16_f32 %0, %1, %2" : "=v"(r) : "v"(lo), "v"(hi)); return r; }
; __device__ __forceinline__ float silu_f(float g) { return g * __builtin_amdgcn_rcpf(1.0f + __expf(-g)); }
; __device__ __forceinline__ float row_rstd(const float* rss, int row) { if (!rss) return 1.0f; const f32x4 s = *(const f32x4*)(rss + 4 * (size_t)row); return __builtin_amdgcn_rsqf(((s[0] + s[1]) + (s[2] + s[3])) * (1.0f / 1024.0f) + 1e-6f); }
;     __device__ __forceinline__ void operator()(const f32x4 (&acc)[2][2][4][2], const Unit& u, int wr, int wc, int fr, int fq) const {
;     ...
;             for (int m = 0; m < 4; ++m) { const int row = row0 + ai * HALF + m * 16; bf16_t* rowp = O + (size_t)row * ldc + col0; const float rs = row_rstd(rss, row);
;                 const f32x4 g0 = acc[ai][0][m][0] * rs, g1 = acc[ai][0][m][1] * rs, u0 = acc[ai][1][m][0] * rs, u1 = acc[ai][1][m][1] * rs;
;                 u32x4 w;
;                 w.x = cvt_pk_bf16(silu_f(g0[0]) * u0[0], silu_f(g0[1]) * u0[1]); w.y = cvt_pk_bf16(silu_f(g0[2]) * u0[2], silu_f(g0[3]) * u0[3]);
;                 w.z = cvt_pk_bf16(silu_f(g1[0]) * u1[0], silu_f(g1[1]) * u1[1]); w.w = cvt_pk_bf16(silu_f(g1[2]) * u1[2], silu_f(g1[3]) * u1[3]);
;                 *(u32x4*)rowp = w; }
	v_mov_b64_e32 v[100:101], v[202:203]
	v_mov_b64_e32 v[102:103], v[204:205]
	v_mov_b32_e32 v104, v101
	v_mov_b32_e32 v105, v102
	v_mov_b32_e32 v101, v103
	v_pk_add_f32 v[100:101], v[104:105], v[100:101]
	s_nop 0
	v_add_f32_e32 v100, v100, v101
	v_fmamk_f32 v100, v100, 0x3a800000, v138
	v_rsq_f32_e32 v100, v100
	s_nop 0
	v_mul_f32_e32 v244, 0xbfb8aa3b, v100
	v_mul_f32_e32 v246, v100, v100
	v_mov_b32_e32 v248, 1.0
	v_pk_mul_f32 v[228:229], v[94:95], v[244:245] op_sel_hi:[1,0]
	v_pk_mul_f32 v[232:233], v[96:97], v[244:245] op_sel_hi:[1,0]
	v_exp_f32_e32 v228, v228
	v_pk_mul_f32 v[236:237], v[90:91], v[244:245] op_sel_hi:[1,0]
	v_exp_f32_e32 v229, v229
	v_pk_mul_f32 v[240:241], v[92:93], v[244:245] op_sel_hi:[1,0]
	v_exp_f32_e32 v232, v232
	v_pk_mul_f32 v[230:231], v[94:95], v[86:87]
	v_exp_f32_e32 v233, v233
	v_pk_mul_f32 v[234:235], v[96:97], v[88:89]
	v_exp_f32_e32 v236, v236
	v_pk_mul_f32 v[238:239], v[90:91], v[82:83]
	v_exp_f32_e32 v237, v237
	v_pk_mul_f32 v[242:243], v[92:93], v[84:85]
	v_exp_f32_e32 v240, v240
	v_pk_add_f32 v[228:229], v[228:229], v[248:249] op_sel_hi:[1,0]
	v_exp_f32_e32 v241, v241
	v_pk_add_f32 v[232:233], v[232:233], v[248:249] op_sel_hi:[1,0]
	v_rcp_f32_e32 v228, v228
	v_pk_add_f32 v[236:237], v[236:237], v[248:249] op_sel_hi:[1,0]
	v_rcp_f32_e32 v229, v229
	v_pk_add_f32 v[240:241], v[240:241], v[248:249] op_sel_hi:[1,0]
	v_rcp_f32_e32 v232, v232
	v_pk_mul_f32 v[230:231], v[230:231], v[246:247] op_sel_hi:[1,0]
	v_rcp_f32_e32 v233, v233
	v_pk_mul_f32 v[234:235], v[234:235], v[246:247] op_sel_hi:[1,0]
	v_rcp_f32_e32 v236, v236
	v_pk_mul_f32 v[238:239], v[238:239], v[246:247] op_sel_hi:[1,0]
	v_rcp_f32_e32 v237, v237
	v_pk_mul_f32 v[242:243], v[242:243], v[246:247] op_sel_hi:[1,0]
	v_rcp_f32_e32 v240, v240
	v_pk_mul_f32 v[230:231], v[230:231], v[228:229]
	v_rcp_f32_e32 v241, v241
	v_pk_mul_f32 v[234:235], v[234:235], v[232:233]
	v_cvt_pk_bf16_f32 v82, v230, v231
	v_pk_mul_f32 v[238:239], v[238:239], v[236:237]
	v_cvt_pk_bf16_f32 v83, v234, v235
	v_pk_mul_f32 v[242:243], v[242:243], v[240:241]
	v_cvt_pk_bf16_f32 v84, v238, v239
	s_nop 0
	v_cvt_pk_bf16_f32 v85, v242, v243
	global_store_dwordx4 v[98:99], v[82:85], off
	s_nop 1
	v_or_b32_e32 v84, 48, v150
	v_ashrrev_i32_e32 v85, 31, v84
	v_mad_i64_i32 v[82:83], s[0:1], v84, s4, v[146:147]
	v_lshl_add_u64 v[84:85], v[84:85], 4, s[22:23]
	v_lshl_add_u64 v[82:83], v[82:83], 0, v[148:149]
	s_waitcnt vmcnt(7)
	v_mov_b64_e32 v[84:85], v[206:207]
	v_mov_b64_e32 v[86:87], v[208:209]
	v_mov_b32_e32 v88, v85
	v_mov_b32_e32 v89, v86
	v_mov_b32_e32 v85, v87
	v_pk_add_f32 v[84:85], v[88:89], v[84:85]
	s_nop 0
	v_add_f32_e32 v84, v84, v85
	v_fmamk_f32 v84, v84, 0x3a800000, v138
	v_rsq_f32_e32 v84, v84
	s_nop 0
	v_mul_f32_e32 v244, 0xbfb8aa3b, v84
	v_mul_f32_e32 v246, v84, v84
	v_mov_b32_e32 v248, 1.0
	v_pk_mul_f32 v[228:229], v[78:79], v[244:245] op_sel_hi:[1,0]
	v_pk_mul_f32 v[232:233], v[80:81], v[244:245] op_sel_hi:[1,0]
	v_exp_f32_e32 v228, v228
	v_pk_mul_f32 v[236:237], v[74:75], v[244:245] op_sel_hi:[1,0]
	v_exp_f32_e32 v229, v229
	v_pk_mul_f32 v[240:241], v[76:77], v[244:245] op_sel_hi:[1,0]
	v_exp_f32_e32 v232, v232
	v_pk_mul_f32 v[230:231], v[78:79], v[70:71]
	v_exp_f32_e32 v233, v233
	v_pk_mul_f32 v[234:235], v[80:81], v[72:73]
	v_exp_f32_e32 v236, v236
	v_pk_mul_f32 v[238:239], v[74:75], v[66:67]
	v_exp_f32_e32 v237, v237
	v_pk_mul_f32 v[242:243], v[76:77], v[68:69]
	v_exp_f32_e32 v240, v240
	v_pk_add_f32 v[228:229], v[228:229], v[248:249] op_sel_hi:[1,0]
	v_exp_f32_e32 v241, v241
	v_pk_add_f32 v[232:233], v[232:233], v[248:249] op_sel_hi:[1,0]
	v_rcp_f32_e32 v228, v228
	v_pk_add_f32 v[236:237], v[236:237], v[248:249] op_sel_hi:[1,0]
	v_rcp_f32_e32 v229, v229
	v_pk_add_f32 v[240:241], v[240:241], v[248:249] op_sel_hi:[1,0]
	v_rcp_f32_e32 v232, v232
	v_pk_mul_f32 v[230:231], v[230:231], v[246:247] op_sel_hi:[1,0]
	v_rcp_f32_e32 v233, v233
	v_pk_mul_f32 v[234:235], v[234:235], v[246:247] op_sel_hi:[1,0]
	v_rcp_f32_e32 v236, v236
	v_pk_mul_f32 v[238:239], v[238:239], v[246:247] op_sel_hi:[1,0]
	v_rcp_f32_e32 v237, v237
	v_pk_mul_f32 v[242:243], v[242:243], v[246:247] op_sel_hi:[1,0]
	v_rcp_f32_e32 v240, v240
	v_pk_mul_f32 v[230:231], v[230:231], v[228:229]
	v_rcp_f32_e32 v241, v241
	v_pk_mul_f32 v[234:235], v[234:235], v[232:233]
	v_cvt_pk_bf16_f32 v66, v230, v231
	v_pk_mul_f32 v[238:239], v[238:239], v[236:237]
	v_cvt_pk_bf16_f32 v67, v234, v235
	v_pk_mul_f32 v[242:243], v[242:243], v[240:241]
	v_cvt_pk_bf16_f32 v68, v238, v239
	s_nop 0
	v_cvt_pk_bf16_f32 v69, v242, v243
	global_store_dwordx4 v[82:83], v[66:69], off
	s_nop 1
	v_add_u32_e32 v68, 0x80, v150
	v_ashrrev_i32_e32 v69, 31, v68
	v_mad_i64_i32 v[66:67], s[0:1], v68, s4, v[146:147]
	v_lshl_add_u64 v[68:69], v[68:69], 4, s[22:23]
	v_lshl_add_u64 v[66:67], v[66:67], 0, v[148:149]
	s_waitcnt vmcnt(7)
; __device__ __forceinline__ unsigned cvt_pk_bf16(float lo, float hi) { unsigned r; asm volatile("v_cvt_pk_bf16_f32 %0, %1, %2" : "=v"(r) : "v"(lo), "v"(hi)); return r; }
; __device__ __forceinline__ float silu_f(float g) { return g * __builtin_amdgcn_rcpf(1.0f + __expf(-g)); }
; __device__ __forceinline__ float row_rstd(const float* rss, int row) { if (!rss) return 1.0f; const f32x4 s = *(const f32x4*)(rss + 4 * (size_t)row); return __builtin_amdgcn_rsqf(((s[0] + s[1]) + (s[2] + s[3])) * (1.0f / 1024.0f) + 1e-6f); }
;     __device__ __forceinline__ void operator()(const f32x4 (&acc)[2][2][4][2], const Unit& u, int wr, int wc, int fr, int fq) const {
;     ...
;             for (int m = 0; m < 4; ++m) { const int row = row0 + ai * HALF + m * 16; bf16_t* rowp = O + (size_t)row * ldc + col0; const float rs = row_rstd(rss, row);
;                 const f32x4 g0 = acc[ai][0][m][0] * rs, g1 = acc[ai][0][m][1] * rs, u0 = acc[ai][1][m][0] * rs, u1 = acc[ai][1][m][1] * rs;
;                 u32x4 w;
;                 w.x = cvt_pk_bf16(silu_f(g0[0]) * u0[0], silu_f(g0[1]) * u0[1]); w.y = cvt_pk_bf16(silu_f(g0[2]) * u0[2], silu_f(g0[3]) * u0[3]);
;                 w.z = cvt_pk_bf16(silu_f(g1[0]) * u1[0], silu_f(g1[1]) * u1[1]); w.w = cvt_pk_bf16(silu_f(g1[2]) * u1[2], silu_f(g1[3]) * u1[3]);
;                 *(u32x4*)rowp = w; }
	v_mov_b64_e32 v[68:69], v[210:211]
	v_mov_b64_e32 v[70:71], v[212:213]
	v_mov_b32_e32 v72, v69
	v_mov_b32_e32 v73, v70
	v_mov_b32_e32 v69, v71
	v_pk_add_f32 v[68:69], v[72:73], v[68:69]
	s_nop 0
	v_add_f32_e32 v68, v68, v69
	v_fmamk_f32 v68, v68, 0x3a800000, v138
	v_rsq_f32_e32 v68, v68
	s_nop 0
	v_mul_f32_e32 v244, 0xbfb8aa3b, v68
	v_mul_f32_e32 v246, v68, v68
	v_mov_b32_e32 v248, 1.0
	v_pk_mul_f32 v[228:229], v[62:63], v[244:245] op_sel_hi:[1,0]
	v_pk_mul_f32 v[232:233], v[64:65], v[244:245] op_sel_hi:[1,0]
	v_exp_f32_e32 v228, v228
	v_pk_mul_f32 v[236:237], v[58:59], v[244:245] op_sel_hi:[1,0]
	v_exp_f32_e32 v229, v229
	v_pk_mul_f32 v[240:241], v[60:61], v[244:245] op_sel_hi:[1,0]
	v_exp_f32_e32 v232, v232
	v_pk_mul_f32 v[230:231], v[62:63], v[54:55]
	v_exp_f32_e32 v233, v233
	v_pk_mul_f32 v[234:235], v[64:65], v[56:57]
	v_exp_f32_e32 v236, v236
	v_pk_mul_f32 v[238:239], v[58:59], v[50:51]
	v_exp_f32_e32 v237, v237
	v_pk_mul_f32 v[242:243], v[60:61], v[52:53]
	v_exp_f32_e32 v240, v240
	v_pk_add_f32 v[228:229], v[228:229], v[248:249] op_sel_hi:[1,0]
	v_exp_f32_e32 v241, v241
	v_pk_add_f32 v[232:233], v[232:233], v[248:249] op_sel_hi:[1,0]
	v_rcp_f32_e32 v228, v228
	v_pk_add_f32 v[236:237], v[236:237], v[248:249] op_sel_hi:[1,0]
	v_rcp_f32_e32 v229, v229
	v_pk_add_f32 v[240:241], v[240:241], v[248:249] op_sel_hi:[1,0]
	v_rcp_f32_e32 v232, v232
	v_pk_mul_f32 v[230:231], v[230:231], v[246:247] op_sel_hi:[1,0]
	v_rcp_f32_e32 v233, v233
	v_pk_mul_f32 v[234:235], v[234:235], v[246:247] op_sel_hi:[1,0]
	v_rcp_f32_e32 v236, v236
	v_pk_mul_f32 v[238:239], v[238:239], v[246:247] op_sel_hi:[1,0]
	v_rcp_f32_e32 v237, v237
	v_pk_mul_f32 v[242:243], v[242:243], v[246:247] op_sel_hi:[1,0]
	v_rcp_f32_e32 v240, v240
	v_pk_mul_f32 v[230:231], v[230:231], v[228:229]
	v_rcp_f32_e32 v241, v241
	v_pk_mul_f32 v[234:235], v[234:235], v[232:233]
	v_cvt_pk_bf16_f32 v50, v230, v231
	v_pk_mul_f32 v[238:239], v[238:239], v[236:237]
	v_cvt_pk_bf16_f32 v51, v234, v235
	v_pk_mul_f32 v[242:243], v[242:243], v[240:241]
	v_cvt_pk_bf16_f32 v52, v238, v239
	s_nop 0
	v_cvt_pk_bf16_f32 v53, v242, v243
	global_store_dwordx4 v[66:67], v[50:53], off
	s_nop 1
	v_add_u32_e32 v52, 0x90, v150
	v_ashrrev_i32_e32 v53, 31, v52
	v_mad_i64_i32 v[50:51], s[0:1], v52, s4, v[146:147]
	v_lshl_add_u64 v[52:53], v[52:53], 4, s[22:23]
	v_lshl_add_u64 v[50:51], v[50:51], 0, v[148:149]
	s_waitcnt vmcnt(7)
	v_mov_b64_e32 v[52:53], v[214:215]
	v_mov_b64_e32 v[54:55], v[216:217]
	v_mov_b32_e32 v56, v53
	v_mov_b32_e32 v57, v54
	v_mov_b32_e32 v53, v55
	v_pk_add_f32 v[52:53], v[56:57], v[52:53]
	s_nop 0
	v_add_f32_e32 v52, v52, v53
	v_fmamk_f32 v52, v52, 0x3a800000, v138
	v_rsq_f32_e32 v52, v52
	s_nop 0
	v_mul_f32_e32 v244, 0xbfb8aa3b, v52
	v_mul_f32_e32 v246, v52, v52
	v_mov_b32_e32 v248, 1.0
	v_pk_mul_f32 v[228:229], v[46:47], v[244:245] op_sel_hi:[1,0]
	v_pk_mul_f32 v[232:233], v[48:49], v[244:245] op_sel_hi:[1,0]
	v_exp_f32_e32 v228, v228
	v_pk_mul_f32 v[236:237], v[42:43], v[244:245] op_sel_hi:[1,0]
	v_exp_f32_e32 v229, v229
	v_pk_mul_f32 v[240:241], v[44:45], v[244:245] op_sel_hi:[1,0]
	v_exp_f32_e32 v232, v232
	v_pk_mul_f32 v[230:231], v[46:47], v[38:39]
	v_exp_f32_e32 v233, v233
	v_pk_mul_f32 v[234:235], v[48:49], v[40:41]
	v_exp_f32_e32 v236, v236
	v_pk_mul_f32 v[238:239], v[42:43], v[34:35]
	v_exp_f32_e32 v237, v237
	v_pk_mul_f32 v[242:243], v[44:45], v[36:37]
	v_exp_f32_e32 v240, v240
	v_pk_add_f32 v[228:229], v[228:229], v[248:249] op_sel_hi:[1,0]
	v_exp_f32_e32 v241, v241
	v_pk_add_f32 v[232:233], v[232:233], v[248:249] op_sel_hi:[1,0]
	v_rcp_f32_e32 v228, v228
	v_pk_add_f32 v[236:237], v[236:237], v[248:249] op_sel_hi:[1,0]
	v_rcp_f32_e32 v229, v229
	v_pk_add_f32 v[240:241], v[240:241], v[248:249] op_sel_hi:[1,0]
	v_rcp_f32_e32 v232, v232
	v_pk_mul_f32 v[230:231], v[230:231], v[246:247] op_sel_hi:[1,0]
	v_rcp_f32_e32 v233, v233
	v_pk_mul_f32 v[234:235], v[234:235], v[246:247] op_sel_hi:[1,0]
	v_rcp_f32_e32 v236, v236
	v_pk_mul_f32 v[238:239], v[238:239], v[246:247] op_sel_hi:[1,0]
	v_rcp_f32_e32 v237, v237
	v_pk_mul_f32 v[242:243], v[242:243], v[246:247] op_sel_hi:[1,0]
	v_rcp_f32_e32 v240, v240
	v_pk_mul_f32 v[230:231], v[230:231], v[228:229]
	v_rcp_f32_e32 v241, v241
	v_pk_mul_f32 v[234:235], v[234:235], v[232:233]
	v_cvt_pk_bf16_f32 v34, v230, v231
	v_pk_mul_f32 v[238:239], v[238:239], v[236:237]
	v_cvt_pk_bf16_f32 v35, v234, v235
	v_pk_mul_f32 v[242:243], v[242:243], v[240:241]
	v_cvt_pk_bf16_f32 v36, v238, v239
	s_nop 0
	v_cvt_pk_bf16_f32 v37, v242, v243
	global_store_dwordx4 v[50:51], v[34:37], off
	s_nop 1
	v_add_u32_e32 v36, 0xa0, v150
	v_ashrrev_i32_e32 v37, 31, v36
	v_mad_i64_i32 v[34:35], s[0:1], v36, s4, v[146:147]
	v_lshl_add_u64 v[36:37], v[36:37], 4, s[22:23]
	v_lshl_add_u64 v[34:35], v[34:35], 0, v[148:149]
	s_waitcnt vmcnt(7)
; __device__ __forceinline__ unsigned cvt_pk_bf16(float lo, float hi) { unsigned r; asm volatile("v_cvt_pk_bf16_f32 %0, %1, %2" : "=v"(r) : "v"(lo), "v"(hi)); return r; }
; __device__ __forceinline__ float silu_f(float g) { return g * __builtin_amdgcn_rcpf(1.0f + __expf(-g)); }
; __device__ __forceinline__ float row_rstd(const float* rss, int row) { if (!rss) return 1.0f; const f32x4 s = *(const f32x4*)(rss + 4 * (size_t)row); return __builtin_amdgcn_rsqf(((s[0] + s[1]) + (s[2] + s[3])) * (1.0f / 1024.0f) + 1e-6f); }
;     __device__ __forceinline__ void operator()(const f32x4 (&acc)[2][2][4][2], const Unit& u, int wr, int wc, int fr, int fq) const {
;     ...
;             for (int m = 0; m < 4; ++m) { const int row = row0 + ai * HALF + m * 16; bf16_t* rowp = O + (size_t)row * ldc + col0; const float rs = row_rstd(rss, row);
;                 const f32x4 g0 = acc[ai][0][m][0] * rs, g1 = acc[ai][0][m][1] * rs, u0 = acc[ai][1][m][0] * rs, u1 = acc[ai][1][m][1] * rs;
;                 u32x4 w;
;                 w.x = cvt_pk_bf16(silu_f(g0[0]) * u0[0], silu_f(g0[1]) * u0[1]); w.y = cvt_pk_bf16(silu_f(g0[2]) * u0[2], silu_f(g0[3]) * u0[3]);
;                 w.z = cvt_pk_bf16(silu_f(g1[0]) * u1[0], silu_f(g1[1]) * u1[1]); w.w = cvt_pk_bf16(silu_f(g1[2]) * u1[2], silu_f(g1[3]) * u1[3]);
;                 *(u32x4*)rowp = w; }
	v_mov_b64_e32 v[36:37], v[218:219]
	v_mov_b64_e32 v[38:39], v[220:221]
	v_mov_b32_e32 v40, v37
	v_mov_b32_e32 v41, v38
	v_mov_b32_e32 v37, v39
	v_pk_add_f32 v[36:37], v[40:41], v[36:37]
	s_nop 0
	v_add_f32_e32 v36, v36, v37
	v_fmamk_f32 v36, v36, 0x3a800000, v138
	v_rsq_f32_e32 v36, v36
	s_nop 0
	v_mul_f32_e32 v244, 0xbfb8aa3b, v36
	v_mul_f32_e32 v246, v36, v36
	v_mov_b32_e32 v248, 1.0
	v_pk_mul_f32 v[228:229], v[30:31], v[244:245] op_sel_hi:[1,0]
	v_pk_mul_f32 v[232:233], v[32:33], v[244:245] op_sel_hi:[1,0]
	v_exp_f32_e32 v228, v228
	v_pk_mul_f32 v[236:237], v[26:27], v[244:245] op_sel_hi:[1,0]
	v_exp_f32_e32 v229, v229
	v_pk_mul_f32 v[240:241], v[28:29], v[244:245] op_sel_hi:[1,0]
	v_exp_f32_e32 v232, v232
	v_pk_mul_f32 v[230:231], v[30:31], v[22:23]
	v_exp_f32_e32 v233, v233
	v_pk_mul_f32 v[234:235], v[32:33], v[24:25]
	v_exp_f32_e32 v236, v236
	v_pk_mul_f32 v[238:239], v[26:27], v[18:19]
	v_exp_f32_e32 v237, v237
	v_pk_mul_f32 v[242:243], v[28:29], v[20:21]
	v_exp_f32_e32 v240, v240
	v_pk_add_f32 v[228:229], v[228:229], v[248:249] op_sel_hi:[1,0]
	v_exp_f32_e32 v241, v241
	v_pk_add_f32 v[232:233], v[232:233], v[248:249] op_sel_hi:[1,0]
	v_rcp_f32_e32 v228, v228
	v_pk_add_f32 v[236:237], v[236:237], v[248:249] op_sel_hi:[1,0]
	v_rcp_f32_e32 v229, v229
	v_pk_add_f32 v[240:241], v[240:241], v[248:249] op_sel_hi:[1,0]
	v_rcp_f32_e32 v232, v232
	v_pk_mul_f32 v[230:231], v[230:231], v[246:247] op_sel_hi:[1,0]
	v_rcp_f32_e32 v233, v233
	v_pk_mul_f32 v[234:235], v[234:235], v[246:247] op_sel_hi:[1,0]
	v_rcp_f32_e32 v236, v236
	v_pk_mul_f32 v[238:239], v[238:239], v[246:247] op_sel_hi:[1,0]
	v_rcp_f32_e32 v237, v237
	v_pk_mul_f32 v[242:243], v[242:243], v[246:247] op_sel_hi:[1,0]
	v_rcp_f32_e32 v240, v240
	v_pk_mul_f32 v[230:231], v[230:231], v[228:229]
	v_rcp_f32_e32 v241, v241
	v_pk_mul_f32 v[234:235], v[234:235], v[232:233]
	v_cvt_pk_bf16_f32 v18, v230, v231
	v_pk_mul_f32 v[238:239], v[238:239], v[236:237]
	v_cvt_pk_bf16_f32 v19, v234, v235
	v_pk_mul_f32 v[242:243], v[242:243], v[240:241]
	v_cvt_pk_bf16_f32 v20, v238, v239
	s_nop 0
	v_cvt_pk_bf16_f32 v21, v242, v243
	global_store_dwordx4 v[34:35], v[18:21], off
	s_nop 1
	v_add_u32_e32 v18, 0xb0, v150
	v_ashrrev_i32_e32 v19, 31, v18
	v_lshl_add_u64 v[20:21], v[18:19], 4, s[22:23]
	s_waitcnt vmcnt(7)
	v_mov_b64_e32 v[20:21], v[222:223]
	v_mov_b64_e32 v[22:23], v[224:225]
	v_mov_b32_e32 v24, v21
	v_mov_b32_e32 v25, v22
	v_mov_b32_e32 v21, v23
	v_pk_add_f32 v[20:21], v[24:25], v[20:21]
	s_nop 0
	v_add_f32_e32 v19, v20, v21
	v_fmamk_f32 v19, v19, 0x3a800000, v138
	v_rsq_f32_e32 v20, v19
	s_nop 0
	v_mad_i64_i32 v[18:19], s[0:1], v18, s4, v[146:147]
	v_lshl_add_u64 v[18:19], v[18:19], 0, v[148:149]
	v_mul_f32_e32 v244, 0xbfb8aa3b, v20
	v_mul_f32_e32 v246, v20, v20
	v_mov_b32_e32 v248, 1.0
	v_pk_mul_f32 v[228:229], v[14:15], v[244:245] op_sel_hi:[1,0]
	v_pk_mul_f32 v[232:233], v[16:17], v[244:245] op_sel_hi:[1,0]
	v_exp_f32_e32 v228, v228
	v_pk_mul_f32 v[236:237], v[10:11], v[244:245] op_sel_hi:[1,0]
	v_exp_f32_e32 v229, v229
	v_pk_mul_f32 v[240:241], v[12:13], v[244:245] op_sel_hi:[1,0]
	v_exp_f32_e32 v232, v232
	v_pk_mul_f32 v[230:231], v[14:15], v[6:7]
	v_exp_f32_e32 v233, v233
	v_pk_mul_f32 v[234:235], v[16:17], v[8:9]
	v_exp_f32_e32 v236, v236
	v_pk_mul_f32 v[238:239], v[10:11], v[2:3]
	v_exp_f32_e32 v237, v237
	v_pk_mul_f32 v[242:243], v[12:13], v[4:5]
	v_exp_f32_e32 v240, v240
	v_pk_add_f32 v[228:229], v[228:229], v[248:249] op_sel_hi:[1,0]
	v_exp_f32_e32 v241, v241
	v_pk_add_f32 v[232:233], v[232:233], v[248:249] op_sel_hi:[1,0]
	v_rcp_f32_e32 v228, v228
	v_pk_add_f32 v[236:237], v[236:237], v[248:249] op_sel_hi:[1,0]
	v_rcp_f32_e32 v229, v229
	v_pk_add_f32 v[240:241], v[240:241], v[248:249] op_sel_hi:[1,0]
	v_rcp_f32_e32 v232, v232
	v_pk_mul_f32 v[230:231], v[230:231], v[246:247] op_sel_hi:[1,0]
	v_rcp_f32_e32 v233, v233
	v_pk_mul_f32 v[234:235], v[234:235], v[246:247] op_sel_hi:[1,0]
	v_rcp_f32_e32 v236, v236
	v_pk_mul_f32 v[238:239], v[238:239], v[246:247] op_sel_hi:[1,0]
	v_rcp_f32_e32 v237, v237
	v_pk_mul_f32 v[242:243], v[242:243], v[246:247] op_sel_hi:[1,0]
	v_rcp_f32_e32 v240, v240
	v_pk_mul_f32 v[230:231], v[230:231], v[228:229]
	v_rcp_f32_e32 v241, v241
	v_pk_mul_f32 v[234:235], v[234:235], v[232:233]
	v_cvt_pk_bf16_f32 v2, v230, v231
	v_pk_mul_f32 v[238:239], v[238:239], v[236:237]
	v_cvt_pk_bf16_f32 v3, v234, v235
	v_pk_mul_f32 v[242:243], v[242:243], v[240:241]
	v_cvt_pk_bf16_f32 v4, v238, v239
	s_nop 0
	v_cvt_pk_bf16_f32 v5, v242, v243
	global_store_dwordx4 v[18:19], v[2:5], off
	s_cbranch_vccnz .LBB0_199
	s_andn2_b64 vcc, exec, s[18:19]
	s_cbranch_vccnz .LBB0_198
	s_barrier
	s_branch .LBB0_198

; __device__ __forceinline__ unsigned cvt_pk_bf16(float lo, float hi) { unsigned r; asm volatile("v_cvt_pk_bf16_f32 %0, %1, %2" : "=v"(r) : "v"(lo), "v"(hi)); return r; }
; __device__ __forceinline__ float silu_f(float g) { return g * __builtin_amdgcn_rcpf(1.0f + __expf(-g)); }
; __device__ __forceinline__ float row_rstd(const float* rss, int row) { if (!rss) return 1.0f; const f32x4 s = *(const f32x4*)(rss + 4 * (size_t)row); return __builtin_amdgcn_rsqf(((s[0] + s[1]) + (s[2] + s[3])) * (1.0f / 1024.0f) + 1e-6f); }
;     __device__ __forceinline__ void operator()(const f32x4 (&acc)[2][2][4][2], const Unit& u, int wr, int wc, int fr, int fq) const {
;     ...
;             for (int m = 0; m < 4; ++m) { const int row = row0 + ai * HALF + m * 16; bf16_t* rowp = O + (size_t)row * ldc + col0; const float rs = row_rstd(rss, row);
;                 const f32x4 g0 = acc[ai][0][m][0] * rs, g1 = acc[ai][0][m][1] * rs, u0 = acc[ai][1][m][0] * rs, u1 = acc[ai][1][m][1] * rs;
;                 u32x4 w;
;                 w.x = cvt_pk_bf16(silu_f(g0[0]) * u0[0], silu_f(g0[1]) * u0[1]); w.y = cvt_pk_bf16(silu_f(g0[2]) * u0[2], silu_f(g0[3]) * u0[3]);
;                 w.z = cvt_pk_bf16(silu_f(g1[0]) * u1[0], silu_f(g1[1]) * u1[1]); w.w = cvt_pk_bf16(silu_f(g1[2]) * u1[2], silu_f(g1[3]) * u1[3]);
;                 *(u32x4*)rowp = w; }
.LBB0_1133:
	v_lshl_or_b32 v146, s0, 7, v151
	v_lshl_add_u32 v148, s1, 8, v1
	v_add_u32_e32 v190, 0, v148
	v_ashrrev_i32_e32 v191, 31, v190
	v_lshl_add_u64 v[190:191], v[190:191], 4, s[24:25]
	global_load_dwordx4 v[190:193], v[190:191], off
	v_add_u32_e32 v194, 16, v148
	v_ashrrev_i32_e32 v195, 31, v194
	v_lshl_add_u64 v[194:195], v[194:195], 4, s[24:25]
	global_load_dwordx4 v[194:197], v[194:195], off
	v_add_u32_e32 v198, 32, v148
	v_ashrrev_i32_e32 v199, 31, v198
	v_lshl_add_u64 v[198:199], v[198:199], 4, s[24:25]
	global_load_dwordx4 v[198:201], v[198:199], off
	v_add_u32_e32 v202, 48, v148
	v_ashrrev_i32_e32 v203, 31, v202
	v_lshl_add_u64 v[202:203], v[202:203], 4, s[24:25]
	global_load_dwordx4 v[202:205], v[202:203], off
	v_add_u32_e32 v206, 128, v148
	v_ashrrev_i32_e32 v207, 31, v206
	v_lshl_add_u64 v[206:207], v[206:207], 4, s[24:25]
	global_load_dwordx4 v[206:209], v[206:207], off
	v_add_u32_e32 v210, 144, v148
	v_ashrrev_i32_e32 v211, 31, v210
	v_lshl_add_u64 v[210:211], v[210:211], 4, s[24:25]
	global_load_dwordx4 v[210:213], v[210:211], off
	v_add_u32_e32 v214, 160, v148
	v_ashrrev_i32_e32 v215, 31, v214
	v_lshl_add_u64 v[214:215], v[214:215], 4, s[24:25]
	global_load_dwordx4 v[214:217], v[214:215], off
	v_add_u32_e32 v218, 176, v148
	v_ashrrev_i32_e32 v219, 31, v218
	v_lshl_add_u64 v[218:219], v[218:219], 4, s[24:25]
	global_load_dwordx4 v[218:221], v[218:219], off
	v_ashrrev_i32_e32 v147, 31, v146
	v_mov_b64_e32 v[144:145], s[22:23]
	v_ashrrev_i32_e32 v149, 31, v148
	v_mad_i64_i32 v[160:161], s[0:1], v148, s4, v[144:145]
	v_lshlrev_b64 v[146:147], 1, v[146:147]
	v_lshl_add_u64 v[164:165], v[160:161], 0, v[146:147]
	v_lshl_add_u64 v[160:161], v[148:149], 4, s[24:25]
	s_mov_b64 s[34:35], -1
	s_and_b64 vcc, exec, s[8:9]
	s_waitcnt vmcnt(7)
	v_mov_b64_e32 v[160:161], v[190:191]
	v_mov_b64_e32 v[162:163], v[192:193]
	v_mov_b32_e32 v166, v161
	v_mov_b32_e32 v167, v162
	v_mov_b32_e32 v161, v163
	v_pk_add_f32 v[160:161], v[166:167], v[160:161]
	s_nop 0
	v_add_f32_e32 v149, v160, v161
	v_fmamk_f32 v149, v149, 0x3a800000, v138
	v_rsq_f32_e32 v160, v149
	s_nop 0
	v_mul_f32_e32 v244, 0xbfb8aa3b, v160
	v_mul_f32_e32 v246, v160, v160
	v_mov_b32_e32 v248, 1.0
	v_pk_mul_f32 v[228:229], v[122:123], v[244:245] op_sel_hi:[1,0]
	v_pk_mul_f32 v[232:233], v[124:125], v[244:245] op_sel_hi:[1,0]
	v_exp_f32_e32 v228, v228
	v_pk_mul_f32 v[236:237], v[126:127], v[244:245] op_sel_hi:[1,0]
	v_exp_f32_e32 v229, v229
	v_pk_mul_f32 v[240:241], v[128:129], v[244:245] op_sel_hi:[1,0]
	v_exp_f32_e32 v232, v232
	v_pk_mul_f32 v[230:231], v[122:123], v[118:119]
	v_exp_f32_e32 v233, v233
	v_pk_mul_f32 v[234:235], v[124:125], v[120:121]
	v_exp_f32_e32 v236, v236
	v_pk_mul_f32 v[238:239], v[126:127], v[114:115]
	v_exp_f32_e32 v237, v237
	v_pk_mul_f32 v[242:243], v[128:129], v[116:117]
	v_exp_f32_e32 v240, v240
	v_pk_add_f32 v[228:229], v[228:229], v[248:249] op_sel_hi:[1,0]
	v_exp_f32_e32 v241, v241
	v_pk_add_f32 v[232:233], v[232:233], v[248:249] op_sel_hi:[1,0]
	v_rcp_f32_e32 v228, v228
	v_pk_add_f32 v[236:237], v[236:237], v[248:249] op_sel_hi:[1,0]
	v_rcp_f32_e32 v229, v229
	v_pk_add_f32 v[240:241], v[240:241], v[248:249] op_sel_hi:[1,0]
	v_rcp_f32_e32 v232, v232
	v_pk_mul_f32 v[230:231], v[230:231], v[246:247] op_sel_hi:[1,0]
	v_rcp_f32_e32 v233, v233
	v_pk_mul_f32 v[234:235], v[234:235], v[246:247] op_sel_hi:[1,0]
	v_rcp_f32_e32 v236, v236
	v_pk_mul_f32 v[238:239], v[238:239], v[246:247] op_sel_hi:[1,0]
	v_rcp_f32_e32 v237, v237
	v_pk_mul_f32 v[242:243], v[242:243], v[246:247] op_sel_hi:[1,0]
	v_rcp_f32_e32 v240, v240
	v_pk_mul_f32 v[230:231], v[230:231], v[228:229]
	v_rcp_f32_e32 v241, v241
	v_pk_mul_f32 v[234:235], v[234:235], v[232:233]
	v_cvt_pk_bf16_f32 v114, v230, v231
	v_pk_mul_f32 v[238:239], v[238:239], v[236:237]
	v_cvt_pk_bf16_f32 v115, v234, v235
	v_pk_mul_f32 v[242:243], v[242:243], v[240:241]
	v_cvt_pk_bf16_f32 v116, v238, v239
	s_nop 0
	v_cvt_pk_bf16_f32 v117, v242, v243
	global_store_dwordx4 v[164:165], v[114:117], off
	s_nop 1
	v_or_b32_e32 v116, 16, v148
	v_ashrrev_i32_e32 v117, 31, v116
	v_mad_i64_i32 v[114:115], s[0:1], v116, s4, v[144:145]
	v_lshl_add_u64 v[116:117], v[116:117], 4, s[24:25]
	v_lshl_add_u64 v[114:115], v[114:115], 0, v[146:147]
	s_waitcnt vmcnt(7)
	v_mov_b64_e32 v[116:117], v[194:195]
	v_mov_b64_e32 v[118:119], v[196:197]
	v_mov_b32_e32 v120, v117
	v_mov_b32_e32 v121, v118
	v_mov_b32_e32 v117, v119
	v_pk_add_f32 v[116:117], v[120:121], v[116:117]
	s_nop 0
	v_add_f32_e32 v116, v116, v117
	v_fmamk_f32 v116, v116, 0x3a800000, v138
	v_rsq_f32_e32 v116, v116
	s_nop 0
	v_mul_f32_e32 v244, 0xbfb8aa3b, v116
	v_mul_f32_e32 v246, v116, v116
	v_mov_b32_e32 v248, 1.0
	v_pk_mul_f32 v[228:229], v[110:111], v[244:245] op_sel_hi:[1,0]
	v_pk_mul_f32 v[232:233], v[112:113], v[244:245] op_sel_hi:[1,0]
	v_exp_f32_e32 v228, v228
	v_pk_mul_f32 v[236:237], v[106:107], v[244:245] op_sel_hi:[1,0]
	v_exp_f32_e32 v229, v229
	v_pk_mul_f32 v[240:241], v[108:109], v[244:245] op_sel_hi:[1,0]
	v_exp_f32_e32 v232, v232
	v_pk_mul_f32 v[230:231], v[110:111], v[102:103]
	v_exp_f32_e32 v233, v233
	v_pk_mul_f32 v[234:235], v[112:113], v[104:105]
	v_exp_f32_e32 v236, v236
	v_pk_mul_f32 v[238:239], v[106:107], v[98:99]
	v_exp_f32_e32 v237, v237
	v_pk_mul_f32 v[242:243], v[108:109], v[100:101]
	v_exp_f32_e32 v240, v240
	v_pk_add_f32 v[228:229], v[228:229], v[248:249] op_sel_hi:[1,0]
	v_exp_f32_e32 v241, v241
	v_pk_add_f32 v[232:233], v[232:233], v[248:249] op_sel_hi:[1,0]
	v_rcp_f32_e32 v228, v228
	v_pk_add_f32 v[236:237], v[236:237], v[248:249] op_sel_hi:[1,0]
	v_rcp_f32_e32 v229, v229
	v_pk_add_f32 v[240:241], v[240:241], v[248:249] op_sel_hi:[1,0]
	v_rcp_f32_e32 v232, v232
	v_pk_mul_f32 v[230:231], v[230:231], v[246:247] op_sel_hi:[1,0]
	v_rcp_f32_e32 v233, v233
	v_pk_mul_f32 v[234:235], v[234:235], v[246:247] op_sel_hi:[1,0]
	v_rcp_f32_e32 v236, v236
	v_pk_mul_f32 v[238:239], v[238:239], v[246:247] op_sel_hi:[1,0]
	v_rcp_f32_e32 v237, v237
	v_pk_mul_f32 v[242:243], v[242:243], v[246:247] op_sel_hi:[1,0]
	v_rcp_f32_e32 v240, v240
	v_pk_mul_f32 v[230:231], v[230:231], v[228:229]
	v_rcp_f32_e32 v241, v241
	v_pk_mul_f32 v[234:235], v[234:235], v[232:233]
	v_cvt_pk_bf16_f32 v98, v230, v231
	v_pk_mul_f32 v[238:239], v[238:239], v[236:237]
	v_cvt_pk_bf16_f32 v99, v234, v235
	v_pk_mul_f32 v[242:243], v[242:243], v[240:241]
	v_cvt_pk_bf16_f32 v100, v238, v239
	s_nop 0
	v_cvt_pk_bf16_f32 v101, v242, v243
	global_store_dwordx4 v[114:115], v[98:101], off
	s_nop 1
	v_or_b32_e32 v100, 32, v148
	v_ashrrev_i32_e32 v101, 31, v100
	v_mad_i64_i32 v[98:99], s[0:1], v100, s4, v[144:145]
	v_lshl_add_u64 v[100:101], v[100:101], 4, s[24:25]
	v_lshl_add_u64 v[98:99], v[98:99], 0, v[146:147]
	s_waitcnt vmcnt(7)
; __device__ __forceinline__ unsigned cvt_pk_bf16(float lo, float hi) { unsigned r; asm volatile("v_cvt_pk_bf16_f32 %0, %1, %2" : "=v"(r) : "v"(lo), "v"(hi)); return r; }
; __device__ __forceinline__ float silu_f(float g) { return g * __builtin_amdgcn_rcpf(1.0f + __expf(-g)); }
; __device__ __forceinline__ float row_rstd(const float* rss, int row) { if (!rss) return 1.0f; const f32x4 s = *(const f32x4*)(rss + 4 * (size_t)row); return __builtin_amdgcn_rsqf(((s[0] + s[1]) + (s[2] + s[3])) * (1.0f / 1024.0f) + 1e-6f); }
;     __device__ __forceinline__ void operator()(const f32x4 (&acc)[2][2][4][2], const Unit& u, int wr, int wc, int fr, int fq) const {
;     ...
;             for (int m = 0; m < 4; ++m) { const int row = row0 + ai * HALF + m * 16; bf16_t* rowp = O + (size_t)row * ldc + col0; const float rs = row_rstd(rss, row);
;                 const f32x4 g0 = acc[ai][0][m][0] * rs, g1 = acc[ai][0][m][1] * rs, u0 = acc[ai][1][m][0] * rs, u1 = acc[ai][1][m][1] * rs;
;                 u32x4 w;
;                 w.x = cvt_pk_bf16(silu_f(g0[0]) * u0[0], silu_f(g0[1]) * u0[1]); w.y = cvt_pk_bf16(silu_f(g0[2]) * u0[2], silu_f(g0[3]) * u0[3]);
;                 w.z = cvt_pk_bf16(silu_f(g1[0]) * u1[0], silu_f(g1[1]) * u1[1]); w.w = cvt_pk_bf16(silu_f(g1[2]) * u1[2], silu_f(g1[3]) * u1[3]);
;                 *(u32x4*)rowp = w; }
	v_mov_b64_e32 v[100:101], v[198:199]
	v_mov_b64_e32 v[102:103], v[200:201]
	v_mov_b32_e32 v104, v101
	v_mov_b32_e32 v105, v102
	v_mov_b32_e32 v101, v103
	v_pk_add_f32 v[100:101], v[104:105], v[100:101]
	s_nop 0
	v_add_f32_e32 v100, v100, v101
	v_fmamk_f32 v100, v100, 0x3a800000, v138
	v_rsq_f32_e32 v100, v100
	s_nop 0
	v_mul_f32_e32 v244, 0xbfb8aa3b, v100
	v_mul_f32_e32 v246, v100, v100
	v_mov_b32_e32 v248, 1.0
	v_pk_mul_f32 v[228:229], v[94:95], v[244:245] op_sel_hi:[1,0]
	v_pk_mul_f32 v[232:233], v[96:97], v[244:245] op_sel_hi:[1,0]
	v_exp_f32_e32 v228, v228
	v_pk_mul_f32 v[236:237], v[90:91], v[244:245] op_sel_hi:[1,0]
	v_exp_f32_e32 v229, v229
	v_pk_mul_f32 v[240:241], v[92:93], v[244:245] op_sel_hi:[1,0]
	v_exp_f32_e32 v232, v232
	v_pk_mul_f32 v[230:231], v[94:95], v[86:87]
	v_exp_f32_e32 v233, v233
	v_pk_mul_f32 v[234:235], v[96:97], v[88:89]
	v_exp_f32_e32 v236, v236
	v_pk_mul_f32 v[238:239], v[90:91], v[82:83]
	v_exp_f32_e32 v237, v237
	v_pk_mul_f32 v[242:243], v[92:93], v[84:85]
	v_exp_f32_e32 v240, v240
	v_pk_add_f32 v[228:229], v[228:229], v[248:249] op_sel_hi:[1,0]
	v_exp_f32_e32 v241, v241
	v_pk_add_f32 v[232:233], v[232:233], v[248:249] op_sel_hi:[1,0]
	v_rcp_f32_e32 v228, v228
	v_pk_add_f32 v[236:237], v[236:237], v[248:249] op_sel_hi:[1,0]
	v_rcp_f32_e32 v229, v229
	v_pk_add_f32 v[240:241], v[240:241], v[248:249] op_sel_hi:[1,0]
	v_rcp_f32_e32 v232, v232
	v_pk_mul_f32 v[230:231], v[230:231], v[246:247] op_sel_hi:[1,0]
	v_rcp_f32_e32 v233, v233
	v_pk_mul_f32 v[234:235], v[234:235], v[246:247] op_sel_hi:[1,0]
	v_rcp_f32_e32 v236, v236
	v_pk_mul_f32 v[238:239], v[238:239], v[246:247] op_sel_hi:[1,0]
	v_rcp_f32_e32 v237, v237
	v_pk_mul_f32 v[242:243], v[242:243], v[246:247] op_sel_hi:[1,0]
	v_rcp_f32_e32 v240, v240
	v_pk_mul_f32 v[230:231], v[230:231], v[228:229]
	v_rcp_f32_e32 v241, v241
	v_pk_mul_f32 v[234:235], v[234:235], v[232:233]
	v_cvt_pk_bf16_f32 v82, v230, v231
	v_pk_mul_f32 v[238:239], v[238:239], v[236:237]
	v_cvt_pk_bf16_f32 v83, v234, v235
	v_pk_mul_f32 v[242:243], v[242:243], v[240:241]
	v_cvt_pk_bf16_f32 v84, v238, v239
	s_nop 0
	v_cvt_pk_bf16_f32 v85, v242, v243
	global_store_dwordx4 v[98:99], v[82:85], off
	s_nop 1
	v_or_b32_e32 v84, 48, v148
	v_ashrrev_i32_e32 v85, 31, v84
	v_mad_i64_i32 v[82:83], s[0:1], v84, s4, v[144:145]
	v_lshl_add_u64 v[84:85], v[84:85], 4, s[24:25]
	v_lshl_add_u64 v[82:83], v[82:83], 0, v[146:147]
	s_waitcnt vmcnt(7)
	v_mov_b64_e32 v[84:85], v[202:203]
	v_mov_b64_e32 v[86:87], v[204:205]
	v_mov_b32_e32 v88, v85
	v_mov_b32_e32 v89, v86
	v_mov_b32_e32 v85, v87
	v_pk_add_f32 v[84:85], v[88:89], v[84:85]
	s_nop 0
	v_add_f32_e32 v84, v84, v85
	v_fmamk_f32 v84, v84, 0x3a800000, v138
	v_rsq_f32_e32 v84, v84
	s_nop 0
	v_mul_f32_e32 v244, 0xbfb8aa3b, v84
	v_mul_f32_e32 v246, v84, v84
	v_mov_b32_e32 v248, 1.0
	v_pk_mul_f32 v[228:229], v[78:79], v[244:245] op_sel_hi:[1,0]
	v_pk_mul_f32 v[232:233], v[80:81], v[244:245] op_sel_hi:[1,0]
	v_exp_f32_e32 v228, v228
	v_pk_mul_f32 v[236:237], v[74:75], v[244:245] op_sel_hi:[1,0]
	v_exp_f32_e32 v229, v229
	v_pk_mul_f32 v[240:241], v[76:77], v[244:245] op_sel_hi:[1,0]
	v_exp_f32_e32 v232, v232
	v_pk_mul_f32 v[230:231], v[78:79], v[70:71]
	v_exp_f32_e32 v233, v233
	v_pk_mul_f32 v[234:235], v[80:81], v[72:73]
	v_exp_f32_e32 v236, v236
	v_pk_mul_f32 v[238:239], v[74:75], v[66:67]
	v_exp_f32_e32 v237, v237
	v_pk_mul_f32 v[242:243], v[76:77], v[68:69]
	v_exp_f32_e32 v240, v240
	v_pk_add_f32 v[228:229], v[228:229], v[248:249] op_sel_hi:[1,0]
	v_exp_f32_e32 v241, v241
	v_pk_add_f32 v[232:233], v[232:233], v[248:249] op_sel_hi:[1,0]
	v_rcp_f32_e32 v228, v228
	v_pk_add_f32 v[236:237], v[236:237], v[248:249] op_sel_hi:[1,0]
	v_rcp_f32_e32 v229, v229
	v_pk_add_f32 v[240:241], v[240:241], v[248:249] op_sel_hi:[1,0]
	v_rcp_f32_e32 v232, v232
	v_pk_mul_f32 v[230:231], v[230:231], v[246:247] op_sel_hi:[1,0]
	v_rcp_f32_e32 v233, v233
	v_pk_mul_f32 v[234:235], v[234:235], v[246:247] op_sel_hi:[1,0]
	v_rcp_f32_e32 v236, v236
	v_pk_mul_f32 v[238:239], v[238:239], v[246:247] op_sel_hi:[1,0]
	v_rcp_f32_e32 v237, v237
	v_pk_mul_f32 v[242:243], v[242:243], v[246:247] op_sel_hi:[1,0]
	v_rcp_f32_e32 v240, v240
	v_pk_mul_f32 v[230:231], v[230:231], v[228:229]
	v_rcp_f32_e32 v241, v241
	v_pk_mul_f32 v[234:235], v[234:235], v[232:233]
	v_cvt_pk_bf16_f32 v66, v230, v231
	v_pk_mul_f32 v[238:239], v[238:239], v[236:237]
	v_cvt_pk_bf16_f32 v67, v234, v235
	v_pk_mul_f32 v[242:243], v[242:243], v[240:241]
	v_cvt_pk_bf16_f32 v68, v238, v239
	s_nop 0
	v_cvt_pk_bf16_f32 v69, v242, v243
	global_store_dwordx4 v[82:83], v[66:69], off
	s_nop 1
	v_add_u32_e32 v68, 0x80, v148
	v_ashrrev_i32_e32 v69, 31, v68
	v_mad_i64_i32 v[66:67], s[0:1], v68, s4, v[144:145]
	v_lshl_add_u64 v[68:69], v[68:69], 4, s[24:25]
	v_lshl_add_u64 v[66:67], v[66:67], 0, v[146:147]
	s_waitcnt vmcnt(7)
; __device__ __forceinline__ unsigned cvt_pk_bf16(float lo, float hi) { unsigned r; asm volatile("v_cvt_pk_bf16_f32 %0, %1, %2" : "=v"(r) : "v"(lo), "v"(hi)); return r; }
; __device__ __forceinline__ float silu_f(float g) { return g * __builtin_amdgcn_rcpf(1.0f + __expf(-g)); }
; __device__ __forceinline__ float row_rstd(const float* rss, int row) { if (!rss) return 1.0f; const f32x4 s = *(const f32x4*)(rss + 4 * (size_t)row); return __builtin_amdgcn_rsqf(((s[0] + s[1]) + (s[2] + s[3])) * (1.0f / 1024.0f) + 1e-6f); }
;     __device__ __forceinline__ void operator()(const f32x4 (&acc)[2][2][4][2], const Unit& u, int wr, int wc, int fr, int fq) const {
;     ...
;             for (int m = 0; m < 4; ++m) { const int row = row0 + ai * HALF + m * 16; bf16_t* rowp = O + (size_t)row * ldc + col0; const float rs = row_rstd(rss, row);
;                 const f32x4 g0 = acc[ai][0][m][0] * rs, g1 = acc[ai][0][m][1] * rs, u0 = acc[ai][1][m][0] * rs, u1 = acc[ai][1][m][1] * rs;
;                 u32x4 w;
;                 w.x = cvt_pk_bf16(silu_f(g0[0]) * u0[0], silu_f(g0[1]) * u0[1]); w.y = cvt_pk_bf16(silu_f(g0[2]) * u0[2], silu_f(g0[3]) * u0[3]);
;                 w.z = cvt_pk_bf16(silu_f(g1[0]) * u1[0], silu_f(g1[1]) * u1[1]); w.w = cvt_pk_bf16(silu_f(g1[2]) * u1[2], silu_f(g1[3]) * u1[3]);
;                 *(u32x4*)rowp = w; }
	v_mov_b64_e32 v[68:69], v[206:207]
	v_mov_b64_e32 v[70:71], v[208:209]
	v_mov_b32_e32 v72, v69
	v_mov_b32_e32 v73, v70
	v_mov_b32_e32 v69, v71
	v_pk_add_f32 v[68:69], v[72:73], v[68:69]
	s_nop 0
	v_add_f32_e32 v68, v68, v69
	v_fmamk_f32 v68, v68, 0x3a800000, v138
	v_rsq_f32_e32 v68, v68
	s_nop 0
	v_mul_f32_e32 v244, 0xbfb8aa3b, v68
	v_mul_f32_e32 v246, v68, v68
	v_mov_b32_e32 v248, 1.0
	v_pk_mul_f32 v[228:229], v[62:63], v[244:245] op_sel_hi:[1,0]
	v_pk_mul_f32 v[232:233], v[64:65], v[244:245] op_sel_hi:[1,0]
	v_exp_f32_e32 v228, v228
	v_pk_mul_f32 v[236:237], v[58:59], v[244:245] op_sel_hi:[1,0]
	v_exp_f32_e32 v229, v229
	v_pk_mul_f32 v[240:241], v[60:61], v[244:245] op_sel_hi:[1,0]
	v_exp_f32_e32 v232, v232
	v_pk_mul_f32 v[230:231], v[62:63], v[54:55]
	v_exp_f32_e32 v233, v233
	v_pk_mul_f32 v[234:235], v[64:65], v[56:57]
	v_exp_f32_e32 v236, v236
	v_pk_mul_f32 v[238:239], v[58:59], v[50:51]
	v_exp_f32_e32 v237, v237
	v_pk_mul_f32 v[242:243], v[60:61], v[52:53]
	v_exp_f32_e32 v240, v240
	v_pk_add_f32 v[228:229], v[228:229], v[248:249] op_sel_hi:[1,0]
	v_exp_f32_e32 v241, v241
	v_pk_add_f32 v[232:233], v[232:233], v[248:249] op_sel_hi:[1,0]
	v_rcp_f32_e32 v228, v228
	v_pk_add_f32 v[236:237], v[236:237], v[248:249] op_sel_hi:[1,0]
	v_rcp_f32_e32 v229, v229
	v_pk_add_f32 v[240:241], v[240:241], v[248:249] op_sel_hi:[1,0]
	v_rcp_f32_e32 v232, v232
	v_pk_mul_f32 v[230:231], v[230:231], v[246:247] op_sel_hi:[1,0]
	v_rcp_f32_e32 v233, v233
	v_pk_mul_f32 v[234:235], v[234:235], v[246:247] op_sel_hi:[1,0]
	v_rcp_f32_e32 v236, v236
	v_pk_mul_f32 v[238:239], v[238:239], v[246:247] op_sel_hi:[1,0]
	v_rcp_f32_e32 v237, v237
	v_pk_mul_f32 v[242:243], v[242:243], v[246:247] op_sel_hi:[1,0]
	v_rcp_f32_e32 v240, v240
	v_pk_mul_f32 v[230:231], v[230:231], v[228:229]
	v_rcp_f32_e32 v241, v241
	v_pk_mul_f32 v[234:235], v[234:235], v[232:233]
	v_cvt_pk_bf16_f32 v50, v230, v231
	v_pk_mul_f32 v[238:239], v[238:239], v[236:237]
	v_cvt_pk_bf16_f32 v51, v234, v235
	v_pk_mul_f32 v[242:243], v[242:243], v[240:241]
	v_cvt_pk_bf16_f32 v52, v238, v239
	s_nop 0
	v_cvt_pk_bf16_f32 v53, v242, v243
	global_store_dwordx4 v[66:67], v[50:53], off
	s_nop 1
	v_add_u32_e32 v52, 0x90, v148
	v_ashrrev_i32_e32 v53, 31, v52
	v_mad_i64_i32 v[50:51], s[0:1], v52, s4, v[144:145]
	v_lshl_add_u64 v[52:53], v[52:53], 4, s[24:25]
	v_lshl_add_u64 v[50:51], v[50:51], 0, v[146:147]
	s_waitcnt vmcnt(7)
	v_mov_b64_e32 v[52:53], v[210:211]
	v_mov_b64_e32 v[54:55], v[212:213]
	v_mov_b32_e32 v56, v53
	v_mov_b32_e32 v57, v54
	v_mov_b32_e32 v53, v55
	v_pk_add_f32 v[52:53], v[56:57], v[52:53]
	s_nop 0
	v_add_f32_e32 v52, v52, v53
	v_fmamk_f32 v52, v52, 0x3a800000, v138
	v_rsq_f32_e32 v52, v52
	s_nop 0
	v_mul_f32_e32 v244, 0xbfb8aa3b, v52
	v_mul_f32_e32 v246, v52, v52
	v_mov_b32_e32 v248, 1.0
	v_pk_mul_f32 v[228:229], v[46:47], v[244:245] op_sel_hi:[1,0]
	v_pk_mul_f32 v[232:233], v[48:49], v[244:245] op_sel_hi:[1,0]
	v_exp_f32_e32 v228, v228
	v_pk_mul_f32 v[236:237], v[42:43], v[244:245] op_sel_hi:[1,0]
	v_exp_f32_e32 v229, v229
	v_pk_mul_f32 v[240:241], v[44:45], v[244:245] op_sel_hi:[1,0]
	v_exp_f32_e32 v232, v232
	v_pk_mul_f32 v[230:231], v[46:47], v[38:39]
	v_exp_f32_e32 v233, v233
	v_pk_mul_f32 v[234:235], v[48:49], v[40:41]
	v_exp_f32_e32 v236, v236
	v_pk_mul_f32 v[238:239], v[42:43], v[34:35]
	v_exp_f32_e32 v237, v237
	v_pk_mul_f32 v[242:243], v[44:45], v[36:37]
	v_exp_f32_e32 v240, v240
	v_pk_add_f32 v[228:229], v[228:229], v[248:249] op_sel_hi:[1,0]
	v_exp_f32_e32 v241, v241
	v_pk_add_f32 v[232:233], v[232:233], v[248:249] op_sel_hi:[1,0]
	v_rcp_f32_e32 v228, v228
	v_pk_add_f32 v[236:237], v[236:237], v[248:249] op_sel_hi:[1,0]
	v_rcp_f32_e32 v229, v229
	v_pk_add_f32 v[240:241], v[240:241], v[248:249] op_sel_hi:[1,0]
	v_rcp_f32_e32 v232, v232
	v_pk_mul_f32 v[230:231], v[230:231], v[246:247] op_sel_hi:[1,0]
	v_rcp_f32_e32 v233, v233
	v_pk_mul_f32 v[234:235], v[234:235], v[246:247] op_sel_hi:[1,0]
	v_rcp_f32_e32 v236, v236
	v_pk_mul_f32 v[238:239], v[238:239], v[246:247] op_sel_hi:[1,0]
	v_rcp_f32_e32 v237, v237
	v_pk_mul_f32 v[242:243], v[242:243], v[246:247] op_sel_hi:[1,0]
	v_rcp_f32_e32 v240, v240
	v_pk_mul_f32 v[230:231], v[230:231], v[228:229]
	v_rcp_f32_e32 v241, v241
	v_pk_mul_f32 v[234:235], v[234:235], v[232:233]
	v_cvt_pk_bf16_f32 v34, v230, v231
	v_pk_mul_f32 v[238:239], v[238:239], v[236:237]
	v_cvt_pk_bf16_f32 v35, v234, v235
	v_pk_mul_f32 v[242:243], v[242:243], v[240:241]
	v_cvt_pk_bf16_f32 v36, v238, v239
	s_nop 0
	v_cvt_pk_bf16_f32 v37, v242, v243
	global_store_dwordx4 v[50:51], v[34:37], off
	s_nop 1
	v_add_u32_e32 v36, 0xa0, v148
	v_ashrrev_i32_e32 v37, 31, v36
	v_mad_i64_i32 v[34:35], s[0:1], v36, s4, v[144:145]
	v_lshl_add_u64 v[36:37], v[36:37], 4, s[24:25]
	v_lshl_add_u64 v[34:35], v[34:35], 0, v[146:147]
	s_waitcnt vmcnt(7)
; __device__ __forceinline__ unsigned cvt_pk_bf16(float lo, float hi) { unsigned r; asm volatile("v_cvt_pk_bf16_f32 %0, %1, %2" : "=v"(r) : "v"(lo), "v"(hi)); return r; }
; __device__ __forceinline__ float silu_f(float g) { return g * __builtin_amdgcn_rcpf(1.0f + __expf(-g)); }
; __device__ __forceinline__ float row_rstd(const float* rss, int row) { if (!rss) return 1.0f; const f32x4 s = *(const f32x4*)(rss + 4 * (size_t)row); return __builtin_amdgcn_rsqf(((s[0] + s[1]) + (s[2] + s[3])) * (1.0f / 1024.0f) + 1e-6f); }
;     __device__ __forceinline__ void operator()(const f32x4 (&acc)[2][2][4][2], const Unit& u, int wr, int wc, int fr, int fq) const {
;     ...
;             for (int m = 0; m < 4; ++m) { const int row = row0 + ai * HALF + m * 16; bf16_t* rowp = O + (size_t)row * ldc + col0; const float rs = row_rstd(rss, row);
;                 const f32x4 g0 = acc[ai][0][m][0] * rs, g1 = acc[ai][0][m][1] * rs, u0 = acc[ai][1][m][0] * rs, u1 = acc[ai][1][m][1] * rs;
;                 u32x4 w;
;                 w.x = cvt_pk_bf16(silu_f(g0[0]) * u0[0], silu_f(g0[1]) * u0[1]); w.y = cvt_pk_bf16(silu_f(g0[2]) * u0[2], silu_f(g0[3]) * u0[3]);
;                 w.z = cvt_pk_bf16(silu_f(g1[0]) * u1[0], silu_f(g1[1]) * u1[1]); w.w = cvt_pk_bf16(silu_f(g1[2]) * u1[2], silu_f(g1[3]) * u1[3]);
;                 *(u32x4*)rowp = w; }
	v_mov_b64_e32 v[36:37], v[214:215]
	v_mov_b64_e32 v[38:39], v[216:217]
	v_mov_b32_e32 v40, v37
	v_mov_b32_e32 v41, v38
	v_mov_b32_e32 v37, v39
	v_pk_add_f32 v[36:37], v[40:41], v[36:37]
	s_nop 0
	v_add_f32_e32 v36, v36, v37
	v_fmamk_f32 v36, v36, 0x3a800000, v138
	v_rsq_f32_e32 v36, v36
	s_nop 0
	v_mul_f32_e32 v244, 0xbfb8aa3b, v36
	v_mul_f32_e32 v246, v36, v36
	v_mov_b32_e32 v248, 1.0
	v_pk_mul_f32 v[228:229], v[30:31], v[244:245] op_sel_hi:[1,0]
	v_pk_mul_f32 v[232:233], v[32:33], v[244:245] op_sel_hi:[1,0]
	v_exp_f32_e32 v228, v228
	v_pk_mul_f32 v[236:237], v[26:27], v[244:245] op_sel_hi:[1,0]
	v_exp_f32_e32 v229, v229
	v_pk_mul_f32 v[240:241], v[28:29], v[244:245] op_sel_hi:[1,0]
	v_exp_f32_e32 v232, v232
	v_pk_mul_f32 v[230:231], v[30:31], v[22:23]
	v_exp_f32_e32 v233, v233
	v_pk_mul_f32 v[234:235], v[32:33], v[24:25]
	v_exp_f32_e32 v236, v236
	v_pk_mul_f32 v[238:239], v[26:27], v[18:19]
	v_exp_f32_e32 v237, v237
	v_pk_mul_f32 v[242:243], v[28:29], v[20:21]
	v_exp_f32_e32 v240, v240
	v_pk_add_f32 v[228:229], v[228:229], v[248:249] op_sel_hi:[1,0]
	v_exp_f32_e32 v241, v241
	v_pk_add_f32 v[232:233], v[232:233], v[248:249] op_sel_hi:[1,0]
	v_rcp_f32_e32 v228, v228
	v_pk_add_f32 v[236:237], v[236:237], v[248:249] op_sel_hi:[1,0]
	v_rcp_f32_e32 v229, v229
	v_pk_add_f32 v[240:241], v[240:241], v[248:249] op_sel_hi:[1,0]
	v_rcp_f32_e32 v232, v232
	v_pk_mul_f32 v[230:231], v[230:231], v[246:247] op_sel_hi:[1,0]
	v_rcp_f32_e32 v233, v233
	v_pk_mul_f32 v[234:235], v[234:235], v[246:247] op_sel_hi:[1,0]
	v_rcp_f32_e32 v236, v236
	v_pk_mul_f32 v[238:239], v[238:239], v[246:247] op_sel_hi:[1,0]
	v_rcp_f32_e32 v237, v237
	v_pk_mul_f32 v[242:243], v[242:243], v[246:247] op_sel_hi:[1,0]
	v_rcp_f32_e32 v240, v240
	v_pk_mul_f32 v[230:231], v[230:231], v[228:229]
	v_rcp_f32_e32 v241, v241
	v_pk_mul_f32 v[234:235], v[234:235], v[232:233]
	v_cvt_pk_bf16_f32 v18, v230, v231
	v_pk_mul_f32 v[238:239], v[238:239], v[236:237]
	v_cvt_pk_bf16_f32 v19, v234, v235
	v_pk_mul_f32 v[242:243], v[242:243], v[240:241]
	v_cvt_pk_bf16_f32 v20, v238, v239
	s_nop 0
	v_cvt_pk_bf16_f32 v21, v242, v243
	global_store_dwordx4 v[34:35], v[18:21], off
	s_nop 1
	v_add_u32_e32 v18, 0xb0, v148
	v_ashrrev_i32_e32 v19, 31, v18
	v_lshl_add_u64 v[20:21], v[18:19], 4, s[24:25]
	s_waitcnt vmcnt(7)
	v_mov_b64_e32 v[20:21], v[218:219]
	v_mov_b64_e32 v[22:23], v[220:221]
	v_mov_b32_e32 v24, v21
	v_mov_b32_e32 v25, v22
	v_mov_b32_e32 v21, v23
	v_pk_add_f32 v[20:21], v[24:25], v[20:21]
	s_nop 0
	v_add_f32_e32 v19, v20, v21
	v_fmamk_f32 v19, v19, 0x3a800000, v138
	v_rsq_f32_e32 v20, v19
	s_nop 0
	v_mad_i64_i32 v[18:19], s[0:1], v18, s4, v[144:145]
	v_lshl_add_u64 v[18:19], v[18:19], 0, v[146:147]
	v_mul_f32_e32 v244, 0xbfb8aa3b, v20
	v_mul_f32_e32 v246, v20, v20
	v_mov_b32_e32 v248, 1.0
	v_pk_mul_f32 v[228:229], v[14:15], v[244:245] op_sel_hi:[1,0]
	v_pk_mul_f32 v[232:233], v[16:17], v[244:245] op_sel_hi:[1,0]
	v_exp_f32_e32 v228, v228
	v_pk_mul_f32 v[236:237], v[10:11], v[244:245] op_sel_hi:[1,0]
	v_exp_f32_e32 v229, v229
	v_pk_mul_f32 v[240:241], v[12:13], v[244:245] op_sel_hi:[1,0]
	v_exp_f32_e32 v232, v232
	v_pk_mul_f32 v[230:231], v[14:15], v[6:7]
	v_exp_f32_e32 v233, v233
	v_pk_mul_f32 v[234:235], v[16:17], v[8:9]
	v_exp_f32_e32 v236, v236
	v_pk_mul_f32 v[238:239], v[10:11], v[2:3]
	v_exp_f32_e32 v237, v237
	v_pk_mul_f32 v[242:243], v[12:13], v[4:5]
	v_exp_f32_e32 v240, v240
	v_pk_add_f32 v[228:229], v[228:229], v[248:249] op_sel_hi:[1,0]
	v_exp_f32_e32 v241, v241
	v_pk_add_f32 v[232:233], v[232:233], v[248:249] op_sel_hi:[1,0]
	v_rcp_f32_e32 v228, v228
	v_pk_add_f32 v[236:237], v[236:237], v[248:249] op_sel_hi:[1,0]
	v_rcp_f32_e32 v229, v229
	v_pk_add_f32 v[240:241], v[240:241], v[248:249] op_sel_hi:[1,0]
	v_rcp_f32_e32 v232, v232
	v_pk_mul_f32 v[230:231], v[230:231], v[246:247] op_sel_hi:[1,0]
	v_rcp_f32_e32 v233, v233
	v_pk_mul_f32 v[234:235], v[234:235], v[246:247] op_sel_hi:[1,0]
	v_rcp_f32_e32 v236, v236
	v_pk_mul_f32 v[238:239], v[238:239], v[246:247] op_sel_hi:[1,0]
	v_rcp_f32_e32 v237, v237
	v_pk_mul_f32 v[242:243], v[242:243], v[246:247] op_sel_hi:[1,0]
	v_rcp_f32_e32 v240, v240
	v_pk_mul_f32 v[230:231], v[230:231], v[228:229]
	v_rcp_f32_e32 v241, v241
	v_pk_mul_f32 v[234:235], v[234:235], v[232:233]
	v_cvt_pk_bf16_f32 v2, v230, v231
	v_pk_mul_f32 v[238:239], v[238:239], v[236:237]
	v_cvt_pk_bf16_f32 v3, v234, v235
	v_pk_mul_f32 v[242:243], v[242:243], v[240:241]
	v_cvt_pk_bf16_f32 v4, v238, v239
	s_nop 0
	v_cvt_pk_bf16_f32 v5, v242, v243
	global_store_dwordx4 v[18:19], v[2:5], off
	s_cbranch_vccnz .LBB0_1121
	s_andn2_b64 vcc, exec, s[20:21]
	s_cbranch_vccnz .LBB0_1120
	s_barrier
	s_branch .LBB0_1120
